# non-temporal stores for the full-line attention outputs (MIX, conv) and the w_down conversion tiles, so seams 3 and 7 have less dirty L2 to write back
# baseline (speedup 1.0000x reference)
.LBB0_398:
	s_or_b64 exec, exec, s[4:5]
	s_waitcnt lgkmcnt(0)
	v_add_u32_e32 v0, s42, v222
	ds_read_b128 v[2:5], v0 offset:128
	ds_read_b128 v[6:9], v0 offset:160
	s_lshl_b32 s4, s68, 6
	s_and_b32 s4, s4, 0xffffe000
	s_add_i32 s64, s64, 1
	s_waitcnt lgkmcnt(1)
	v_rcp_f32_e32 v10, v2
	v_rcp_f32_e32 v11, v3
	v_rcp_f32_e32 v12, v4
	v_rcp_f32_e32 v13, v5
	s_waitcnt lgkmcnt(0)
	v_rcp_f32_e32 v14, v6
	ds_read_b128 v[2:5], v0 offset:192
	v_rcp_f32_e32 v15, v7
	v_rcp_f32_e32 v80, v8
	v_rcp_f32_e32 v81, v9
	ds_read_b128 v[6:9], v0 offset:224
	v_mul_f32_e32 v16, v16, v10
	s_waitcnt lgkmcnt(1)
	v_rcp_f32_e32 v0, v2
	v_rcp_f32_e32 v2, v3
	v_rcp_f32_e32 v3, v4
	v_rcp_f32_e32 v4, v5
	s_waitcnt lgkmcnt(0)
	v_rcp_f32_e32 v5, v6
	v_rcp_f32_e32 v6, v7
	v_rcp_f32_e32 v7, v8
	v_rcp_f32_e32 v8, v9
	v_lshl_add_u32 v9, s70, 13, v223
	v_cvt_pk_bf16_f32 v16, v16, s0
	s_waitcnt vmcnt(0) lgkmcnt(0)
	s_barrier
	ds_write_b16 v9, v16
	v_mul_f32_e32 v16, v32, v10
	v_cvt_pk_bf16_f32 v16, v16, s0
	ds_write_b16 v9, v16 offset:64
	v_mul_f32_e32 v16, v48, v10
	v_mul_f32_e32 v10, v64, v10
	v_cvt_pk_bf16_f32 v10, v10, s0
	ds_write_b16 v9, v10 offset:192
	v_mul_f32_e32 v10, v17, v11
	v_cvt_pk_bf16_f32 v10, v10, s0
	ds_write_b16 v9, v10 offset:256
	v_mul_f32_e32 v10, v33, v11
	v_cvt_pk_bf16_f32 v10, v10, s0
	ds_write_b16 v9, v10 offset:320
	v_mul_f32_e32 v10, v49, v11
	v_cvt_pk_bf16_f32 v10, v10, s0
	ds_write_b16 v9, v10 offset:384
	v_mul_f32_e32 v10, v65, v11
	v_cvt_pk_bf16_f32 v10, v10, s0
	ds_write_b16 v9, v10 offset:448
	v_mul_f32_e32 v10, v18, v12
	v_cvt_pk_bf16_f32 v10, v10, s0
	ds_write_b16 v9, v10 offset:512
	v_mul_f32_e32 v10, v34, v12
	v_cvt_pk_bf16_f32 v10, v10, s0
	ds_write_b16 v9, v10 offset:576
	v_mul_f32_e32 v10, v50, v12
	v_cvt_pk_bf16_f32 v10, v10, s0
	ds_write_b16 v9, v10 offset:640
	v_mul_f32_e32 v10, v66, v12
	v_cvt_pk_bf16_f32 v10, v10, s0
	ds_write_b16 v9, v10 offset:704
	v_mul_f32_e32 v10, v19, v13
	v_cvt_pk_bf16_f32 v10, v10, s0
	ds_write_b16 v9, v10 offset:768
	v_mul_f32_e32 v10, v35, v13
	v_cvt_pk_bf16_f32 v10, v10, s0
	ds_write_b16 v9, v10 offset:832
	v_mul_f32_e32 v10, v51, v13
	v_cvt_pk_bf16_f32 v10, v10, s0
	ds_write_b16 v9, v10 offset:896
	v_mul_f32_e32 v10, v67, v13
	v_cvt_pk_bf16_f32 v10, v10, s0
	ds_write_b16 v9, v10 offset:960
	v_mul_f32_e32 v10, v20, v14
	v_cvt_pk_bf16_f32 v10, v10, s0
	ds_write_b16 v9, v10 offset:2048
	v_mul_f32_e32 v10, v36, v14
	v_cvt_pk_bf16_f32 v10, v10, s0
	ds_write_b16 v9, v10 offset:2112
	v_mul_f32_e32 v10, v52, v14
	v_cvt_pk_bf16_f32 v10, v10, s0
	ds_write_b16 v9, v10 offset:2176
	v_mul_f32_e32 v10, v68, v14
	v_cvt_pk_bf16_f32 v10, v10, s0
	ds_write_b16 v9, v10 offset:2240
	v_mul_f32_e32 v10, v21, v15
	v_cvt_pk_bf16_f32 v10, v10, s0
	ds_write_b16 v9, v10 offset:2304
	v_mul_f32_e32 v10, v37, v15
	v_cvt_pk_bf16_f32 v10, v10, s0
	ds_write_b16 v9, v10 offset:2368
	v_mul_f32_e32 v10, v53, v15
	v_cvt_pk_bf16_f32 v10, v10, s0
	ds_write_b16 v9, v10 offset:2432
	v_mul_f32_e32 v10, v69, v15
	v_cvt_pk_bf16_f32 v10, v10, s0
	ds_write_b16 v9, v10 offset:2496
	v_mul_f32_e32 v10, v22, v80
	v_cvt_pk_bf16_f32 v10, v10, s0
	ds_write_b16 v9, v10 offset:2560
	v_mul_f32_e32 v10, v38, v80
	v_cvt_pk_bf16_f32 v10, v10, s0
	ds_write_b16 v9, v10 offset:2624
	v_mul_f32_e32 v10, v54, v80
	v_cvt_pk_bf16_f32 v10, v10, s0
	ds_write_b16 v9, v10 offset:2688
	v_mul_f32_e32 v10, v70, v80
	v_cvt_pk_bf16_f32 v10, v10, s0
	ds_write_b16 v9, v10 offset:2752
	v_mul_f32_e32 v10, v23, v81
	v_cvt_pk_bf16_f32 v10, v10, s0
	ds_write_b16 v9, v10 offset:2816
	v_mul_f32_e32 v10, v39, v81
	v_cvt_pk_bf16_f32 v10, v10, s0
	ds_write_b16 v9, v10 offset:2880
	v_mul_f32_e32 v10, v55, v81
	v_cvt_pk_bf16_f32 v10, v10, s0
	ds_write_b16 v9, v10 offset:2944
	v_mul_f32_e32 v10, v71, v81
	v_cvt_pk_bf16_f32 v10, v10, s0
	ds_write_b16 v9, v10 offset:3008
	v_mul_f32_e32 v10, v24, v0
	v_cvt_pk_bf16_f32 v10, v10, s0
	ds_write_b16 v9, v10 offset:4096
	v_mul_f32_e32 v10, v40, v0
	v_cvt_pk_bf16_f32 v10, v10, s0
	ds_write_b16 v9, v10 offset:4160
	v_mul_f32_e32 v10, v56, v0
	v_mul_f32_e32 v0, v72, v0
	v_cvt_pk_bf16_f32 v0, v0, s0
	ds_write_b16 v9, v0 offset:4288
	v_mul_f32_e32 v0, v25, v2
	v_cvt_pk_bf16_f32 v0, v0, s0
	ds_write_b16 v9, v0 offset:4352
	v_mul_f32_e32 v0, v41, v2
	v_cvt_pk_bf16_f32 v0, v0, s0
	ds_write_b16 v9, v0 offset:4416
	v_mul_f32_e32 v0, v57, v2
	v_cvt_pk_bf16_f32 v0, v0, s0
	ds_write_b16 v9, v0 offset:4480
	v_mul_f32_e32 v0, v73, v2
	v_cvt_pk_bf16_f32 v0, v0, s0
	ds_write_b16 v9, v0 offset:4544
	v_mul_f32_e32 v0, v26, v3
	v_cvt_pk_bf16_f32 v0, v0, s0
	ds_write_b16 v9, v0 offset:4608
	v_mul_f32_e32 v0, v42, v3
	v_cvt_pk_bf16_f32 v0, v0, s0
	ds_write_b16 v9, v0 offset:4672
	v_mul_f32_e32 v0, v58, v3
	v_cvt_pk_bf16_f32 v0, v0, s0
	ds_write_b16 v9, v0 offset:4736
	v_mul_f32_e32 v0, v74, v3
	v_cvt_pk_bf16_f32 v0, v0, s0
	ds_write_b16 v9, v0 offset:4800
	v_mul_f32_e32 v0, v27, v4
	v_cvt_pk_bf16_f32 v0, v0, s0
	ds_write_b16 v9, v0 offset:4864
	v_mul_f32_e32 v0, v43, v4
	v_cvt_pk_bf16_f32 v0, v0, s0
	ds_write_b16 v9, v0 offset:4928
	v_mul_f32_e32 v0, v59, v4
	v_cvt_pk_bf16_f32 v0, v0, s0
	ds_write_b16 v9, v0 offset:4992
	v_mul_f32_e32 v0, v75, v4
	v_cvt_pk_bf16_f32 v0, v0, s0
	ds_write_b16 v9, v0 offset:5056
	v_mul_f32_e32 v0, v28, v5
	v_cvt_pk_bf16_f32 v0, v0, s0
	ds_write_b16 v9, v0 offset:6144
	v_mul_f32_e32 v0, v44, v5
	v_cvt_pk_bf16_f32 v0, v0, s0
	ds_write_b16 v9, v0 offset:6208
	v_mul_f32_e32 v0, v60, v5
	v_cvt_pk_bf16_f32 v0, v0, s0
	ds_write_b16 v9, v0 offset:6272
	v_mul_f32_e32 v0, v76, v5
	v_cvt_pk_bf16_f32 v0, v0, s0
	ds_write_b16 v9, v0 offset:6336
	v_mul_f32_e32 v0, v29, v6
	v_cvt_pk_bf16_f32 v0, v0, s0
	ds_write_b16 v9, v0 offset:6400
	v_mul_f32_e32 v0, v45, v6
	v_cvt_pk_bf16_f32 v0, v0, s0
	ds_write_b16 v9, v0 offset:6464
	v_mul_f32_e32 v0, v61, v6
	v_cvt_pk_bf16_f32 v0, v0, s0
	ds_write_b16 v9, v0 offset:6528
	v_mul_f32_e32 v0, v77, v6
	v_cvt_pk_bf16_f32 v0, v0, s0
	ds_write_b16 v9, v0 offset:6592
	v_mul_f32_e32 v0, v30, v7
	v_cvt_pk_bf16_f32 v0, v0, s0
	ds_write_b16 v9, v0 offset:6656
	v_mul_f32_e32 v0, v46, v7
	v_cvt_pk_bf16_f32 v0, v0, s0
	ds_write_b16 v9, v0 offset:6720
	v_mul_f32_e32 v0, v62, v7
	v_cvt_pk_bf16_f32 v0, v0, s0
	ds_write_b16 v9, v0 offset:6784
	v_mul_f32_e32 v0, v78, v7
	v_cvt_pk_bf16_f32 v0, v0, s0
	ds_write_b16 v9, v0 offset:6848
	v_mul_f32_e32 v0, v31, v8
	v_cvt_pk_bf16_f32 v0, v0, s0
	ds_write_b16 v9, v0 offset:6912
	v_mul_f32_e32 v0, v47, v8
	v_cvt_pk_bf16_f32 v0, v0, s0
	ds_write_b16 v9, v0 offset:6976
	v_mul_f32_e32 v0, v63, v8
	v_cvt_pk_bf16_f32 v0, v0, s0
	ds_write_b16 v9, v0 offset:7040
	v_mul_f32_e32 v0, v79, v8
	v_cvt_pk_bf16_f32 v0, v0, s0
	ds_write_b16 v9, v0 offset:7104
	v_or_b32_e32 v0, s69, v217
	v_cvt_pk_bf16_f32 v16, v16, s0
	v_cvt_pk_bf16_f32 v10, v10, s0
	v_lshlrev_b32_e32 v2, 8, v0
	ds_write_b16 v9, v16 offset:128
	ds_write_b16 v9, v10 offset:4224
	v_add_u32_e32 v34, s4, v206
	v_and_b32_e32 v2, 0x1300, v2
	s_waitcnt lgkmcnt(0)
	s_barrier
	v_add_u32_e32 v6, v34, v2
	ds_read_b128 v[2:5], v6
	ds_read_b128 v[6:9], v6 offset:32768
	v_or_b32_e32 v20, 4, v0
	s_waitcnt lgkmcnt(1)
	v_lshlrev_b32_e32 v10, 16, v5
	v_and_b32_e32 v11, 0xffff0000, v5
	s_waitcnt lgkmcnt(0)
	v_lshlrev_b32_e32 v12, 16, v9
	v_and_b32_e32 v13, 0xffff0000, v9
	v_lshlrev_b32_e32 v14, 16, v4
	v_and_b32_e32 v15, 0xffff0000, v4
	v_lshlrev_b32_e32 v4, 16, v8
	v_and_b32_e32 v5, 0xffff0000, v8
	v_lshlrev_b32_e32 v8, 16, v3
	v_and_b32_e32 v9, 0xffff0000, v3
	v_lshlrev_b32_e32 v18, 16, v2
	v_and_b32_e32 v19, 0xffff0000, v2
	v_lshlrev_b32_e32 v2, 16, v6
	v_and_b32_e32 v3, 0xffff0000, v6
	v_lshlrev_b32_e32 v16, 16, v7
	v_and_b32_e32 v17, 0xffff0000, v7
	v_pk_fma_f32 v[18:19], v[186:187], v[2:3], v[18:19] neg_lo:[1,0,0] neg_hi:[1,0,0]
	v_pk_fma_f32 v[16:17], v[186:187], v[16:17], v[8:9] neg_lo:[1,0,0] neg_hi:[1,0,0]
	v_pk_mul_f32 v[2:3], v[18:19], v[18:19]
	v_pk_mul_f32 v[8:9], v[16:17], v[16:17]
	v_add_f32_e32 v2, v2, v3
	v_pk_fma_f32 v[14:15], v[186:187], v[4:5], v[14:15] neg_lo:[1,0,0] neg_hi:[1,0,0]
	v_add_f32_e32 v2, v8, v2
	v_pk_mul_f32 v[4:5], v[14:15], v[14:15]
	v_add_f32_e32 v2, v9, v2
	v_pk_fma_f32 v[12:13], v[186:187], v[12:13], v[10:11] neg_lo:[1,0,0] neg_hi:[1,0,0]
	v_add_f32_e32 v2, v4, v2
	v_pk_mul_f32 v[10:11], v[12:13], v[12:13]
	v_add_f32_e32 v2, v5, v2
	v_add_f32_e32 v2, v10, v2
	v_add_f32_e32 v2, v11, v2
	s_nop 1
	v_mov_b32_dpp v3, v2 quad_perm:[1,0,3,2] row_mask:0xf bank_mask:0xf
	s_waitcnt lgkmcnt(0)
	v_add_f32_e32 v2, v2, v3
	s_nop 1
	v_mov_b32_dpp v3, v2 quad_perm:[2,3,0,1] row_mask:0xf bank_mask:0xf
	s_waitcnt lgkmcnt(0)
	v_add_f32_e32 v2, v2, v3
	s_nop 1
	v_mov_b32_dpp v3, v2 row_half_mirror row_mask:0xf bank_mask:0xf
	s_waitcnt lgkmcnt(0)
	v_add_f32_e32 v2, v2, v3
	s_nop 1
	v_mov_b32_dpp v3, v2 row_mirror row_mask:0xf bank_mask:0xf
	s_waitcnt lgkmcnt(0)
	v_add_f32_e32 v2, v2, v3
	v_fmamk_f32 v2, v2, 0x3c000000, v207
	v_mul_f32_e32 v3, 0x4f800000, v2
	v_cmp_gt_f32_e32 vcc, s63, v2
	s_nop 1
	v_cndmask_b32_e32 v4, v2, v3, vcc
	v_sqrt_f32_e32 v5, v4
	v_lshl_add_u64 v[2:3], v[188:189], 0, s[38:39]
	v_add_u32_e32 v6, -1, v5
	v_fma_f32 v7, -v6, v5, v4
	v_cmp_ge_f32_e64 s[4:5], 0, v7
	v_add_u32_e32 v7, 1, v5
	s_nop 0
	v_cndmask_b32_e64 v6, v5, v6, s[4:5]
	v_fma_f32 v5, -v7, v5, v4
	v_cmp_lt_f32_e64 s[4:5], 0, v5
	s_nop 1
	v_cndmask_b32_e64 v5, v6, v7, s[4:5]
	v_mul_f32_e32 v6, 0x37800000, v5
	v_cndmask_b32_e32 v5, v5, v6, vcc
	v_cmp_class_f32_e32 vcc, v4, v224
	s_nop 1
	v_cndmask_b32_e32 v21, v5, v4, vcc
	v_lshlrev_b32_e32 v4, 8, v20
	v_and_b32_e32 v4, 0x1700, v4
	v_add_u32_e32 v8, v34, v4
	ds_read_b128 v[4:7], v8
	ds_read_b128 v[8:11], v8 offset:32768
	v_div_scale_f32 v32, s[4:5], v21, v21, 1.0
	v_rcp_f32_e32 v33, v32
	s_waitcnt lgkmcnt(1)
	v_lshlrev_b32_e32 v22, 16, v7
	v_and_b32_e32 v23, 0xffff0000, v7
	s_waitcnt lgkmcnt(0)
	v_lshlrev_b32_e32 v24, 16, v11
	v_and_b32_e32 v25, 0xffff0000, v11
	v_lshlrev_b32_e32 v26, 16, v6
	v_and_b32_e32 v27, 0xffff0000, v6
	v_lshlrev_b32_e32 v6, 16, v10
	v_and_b32_e32 v7, 0xffff0000, v10
	v_lshlrev_b32_e32 v10, 16, v5
	v_and_b32_e32 v11, 0xffff0000, v5
	v_lshlrev_b32_e32 v30, 16, v4
	v_and_b32_e32 v31, 0xffff0000, v4
	v_lshlrev_b32_e32 v4, 16, v8
	v_and_b32_e32 v5, 0xffff0000, v8
	v_lshlrev_b32_e32 v28, 16, v9
	v_and_b32_e32 v29, 0xffff0000, v9
	v_pk_fma_f32 v[30:31], v[186:187], v[4:5], v[30:31] neg_lo:[1,0,0] neg_hi:[1,0,0]
	v_pk_fma_f32 v[28:29], v[186:187], v[28:29], v[10:11] neg_lo:[1,0,0] neg_hi:[1,0,0]
	v_pk_mul_f32 v[4:5], v[30:31], v[30:31]
	v_pk_mul_f32 v[10:11], v[28:29], v[28:29]
	v_add_f32_e32 v4, v4, v5
	v_pk_fma_f32 v[26:27], v[186:187], v[6:7], v[26:27] neg_lo:[1,0,0] neg_hi:[1,0,0]
	v_add_f32_e32 v4, v10, v4
	v_pk_mul_f32 v[6:7], v[26:27], v[26:27]
	v_add_f32_e32 v4, v11, v4
	v_pk_fma_f32 v[22:23], v[186:187], v[24:25], v[22:23] neg_lo:[1,0,0] neg_hi:[1,0,0]
	v_add_f32_e32 v4, v6, v4
	v_pk_mul_f32 v[24:25], v[22:23], v[22:23]
	v_add_f32_e32 v4, v7, v4
	v_add_f32_e32 v4, v24, v4
	v_add_f32_e32 v4, v25, v4
	s_nop 1
	v_mov_b32_dpp v5, v4 quad_perm:[1,0,3,2] row_mask:0xf bank_mask:0xf
	v_fma_f32 v6, -v32, v33, 1.0
	v_fmac_f32_e32 v33, v6, v33
	v_div_scale_f32 v6, vcc, 1.0, v21, 1.0
	s_waitcnt lgkmcnt(0)
	v_add_f32_e32 v4, v4, v5
	s_nop 1
	v_mov_b32_dpp v5, v4 quad_perm:[2,3,0,1] row_mask:0xf bank_mask:0xf
	v_mul_f32_e32 v7, v6, v33
	v_fma_f32 v8, -v32, v7, v6
	v_fmac_f32_e32 v7, v8, v33
	v_fma_f32 v6, -v32, v7, v6
	s_waitcnt lgkmcnt(0)
	v_add_f32_e32 v9, v4, v5
	s_nop 1
	v_mov_b32_dpp v10, v9 row_half_mirror row_mask:0xf bank_mask:0xf
	v_div_fmas_f32 v4, v6, v33, v7
	v_div_fixup_f32 v8, v4, v21, 1.0
	v_pk_mul_f32 v[4:5], v[18:19], v[8:9] op_sel_hi:[1,0]
	s_waitcnt lgkmcnt(0)
	v_add_f32_e32 v9, v9, v10
	s_nop 1
	v_mov_b32_dpp v10, v9 row_mirror row_mask:0xf bank_mask:0xf
	v_pk_mul_f32 v[6:7], v[16:17], v[8:9] op_sel_hi:[1,0]
	v_cvt_pk_bf16_f32 v4, v4, v5
	v_cvt_pk_bf16_f32 v5, v6, v7
	v_pk_mul_f32 v[6:7], v[14:15], v[8:9] op_sel_hi:[1,0]
	s_nop 0
	v_cvt_pk_bf16_f32 v6, v6, v7
	s_waitcnt lgkmcnt(0)
	v_add_f32_e32 v7, v9, v10
	v_fmamk_f32 v7, v7, 0x3c000000, v207
	v_mul_f32_e32 v9, 0x4f800000, v7
	v_cmp_gt_f32_e32 vcc, s63, v7
	s_nop 1
	v_cndmask_b32_e32 v10, v7, v9, vcc
	v_sqrt_f32_e32 v11, v10
	v_pk_mul_f32 v[8:9], v[12:13], v[8:9] op_sel_hi:[1,0]
	v_add_u32_e32 v12, -1, v11
	v_fma_f32 v13, -v12, v11, v10
	v_cmp_ge_f32_e64 s[4:5], 0, v13
	v_add_u32_e32 v13, 1, v11
	v_cvt_pk_bf16_f32 v7, v8, v9
	v_cndmask_b32_e64 v12, v11, v12, s[4:5]
	v_fma_f32 v11, -v13, v11, v10
	v_cmp_lt_f32_e64 s[4:5], 0, v11
	v_lshl_add_u64 v[8:9], s[40:41], 0, v[0:1]
	v_lshlrev_b64 v[8:9], 12, v[8:9]
	v_cndmask_b32_e64 v11, v12, v13, s[4:5]
	v_mul_f32_e32 v12, 0x37800000, v11
	v_cndmask_b32_e32 v11, v11, v12, vcc
	v_cmp_class_f32_e32 vcc, v10, v224
	v_lshl_add_u64 v[8:9], v[2:3], 0, v[8:9]
	v_or_b32_e32 v12, 8, v0
	v_cndmask_b32_e32 v13, v11, v10, vcc
	v_div_scale_f32 v21, s[4:5], v13, v13, 1.0
	v_rcp_f32_e32 v35, v21
	global_store_dwordx4 v[8:9], v[4:7], off nt
	v_div_scale_f32 v36, vcc, 1.0, v13, 1.0
	s_nop 0
	v_lshlrev_b32_e32 v4, 8, v12
	v_and_b32_e32 v4, 0x1b00, v4
	v_fma_f32 v8, -v21, v35, 1.0
	v_add_u32_e32 v9, v34, v4
	ds_read_b128 v[4:7], v9
	v_fmac_f32_e32 v35, v8, v35
	ds_read_b128 v[8:11], v9 offset:32768
	v_or_b32_e32 v0, 12, v0
	s_waitcnt lgkmcnt(1)
	v_lshlrev_b32_e32 v14, 16, v7
	v_and_b32_e32 v15, 0xffff0000, v7
	s_waitcnt lgkmcnt(0)
	v_lshlrev_b32_e32 v16, 16, v11
	v_and_b32_e32 v17, 0xffff0000, v11
	v_lshlrev_b32_e32 v18, 16, v6
	v_and_b32_e32 v19, 0xffff0000, v6
	v_lshlrev_b32_e32 v6, 16, v10
	v_and_b32_e32 v7, 0xffff0000, v10
	v_lshlrev_b32_e32 v10, 16, v5
	v_and_b32_e32 v11, 0xffff0000, v5
	v_lshlrev_b32_e32 v32, 16, v4
	v_and_b32_e32 v33, 0xffff0000, v4
	v_lshlrev_b32_e32 v4, 16, v8
	v_and_b32_e32 v5, 0xffff0000, v8
	v_lshlrev_b32_e32 v24, 16, v9
	v_and_b32_e32 v25, 0xffff0000, v9
	v_pk_fma_f32 v[32:33], v[186:187], v[4:5], v[32:33] neg_lo:[1,0,0] neg_hi:[1,0,0]
	v_pk_fma_f32 v[24:25], v[186:187], v[24:25], v[10:11] neg_lo:[1,0,0] neg_hi:[1,0,0]
	v_pk_mul_f32 v[4:5], v[32:33], v[32:33]
	v_pk_mul_f32 v[10:11], v[24:25], v[24:25]
	v_add_f32_e32 v4, v4, v5
	v_pk_fma_f32 v[18:19], v[186:187], v[6:7], v[18:19] neg_lo:[1,0,0] neg_hi:[1,0,0]
	v_add_f32_e32 v4, v10, v4
	v_pk_mul_f32 v[6:7], v[18:19], v[18:19]
	v_add_f32_e32 v4, v11, v4
	v_pk_fma_f32 v[14:15], v[186:187], v[16:17], v[14:15] neg_lo:[1,0,0] neg_hi:[1,0,0]
	v_add_f32_e32 v4, v6, v4
	v_pk_mul_f32 v[16:17], v[14:15], v[14:15]
	v_add_f32_e32 v4, v7, v4
	v_add_f32_e32 v4, v16, v4
	v_add_f32_e32 v4, v17, v4
	s_nop 1
	v_mov_b32_dpp v5, v4 quad_perm:[1,0,3,2] row_mask:0xf bank_mask:0xf
	v_mul_f32_e32 v6, v36, v35
	v_fma_f32 v7, -v21, v6, v36
	v_fmac_f32_e32 v6, v7, v35
	v_fma_f32 v7, -v21, v6, v36
	s_waitcnt lgkmcnt(0)
	v_add_f32_e32 v9, v4, v5
	s_nop 1
	v_mov_b32_dpp v10, v9 quad_perm:[2,3,0,1] row_mask:0xf bank_mask:0xf
	v_div_fmas_f32 v4, v7, v35, v6
	v_div_fixup_f32 v8, v4, v13, 1.0
	v_pk_mul_f32 v[4:5], v[30:31], v[8:9] op_sel_hi:[1,0]
	v_mov_b32_e32 v21, v1
	s_waitcnt lgkmcnt(0)
	v_add_f32_e32 v9, v9, v10
	s_nop 1
	v_mov_b32_dpp v10, v9 row_half_mirror row_mask:0xf bank_mask:0xf
	v_pk_mul_f32 v[6:7], v[28:29], v[8:9] op_sel_hi:[1,0]
	v_cvt_pk_bf16_f32 v4, v4, v5
	v_cvt_pk_bf16_f32 v5, v6, v7
	v_pk_mul_f32 v[6:7], v[26:27], v[8:9] op_sel_hi:[1,0]
	s_waitcnt lgkmcnt(0)
	v_add_f32_e32 v10, v9, v10
	s_nop 1
	v_mov_b32_dpp v11, v10 row_mirror row_mask:0xf bank_mask:0xf
	v_pk_mul_f32 v[8:9], v[22:23], v[8:9] op_sel_hi:[1,0]
	v_cvt_pk_bf16_f32 v6, v6, v7
	v_cvt_pk_bf16_f32 v7, v8, v9
	s_waitcnt lgkmcnt(0)
	v_add_f32_e32 v8, v10, v11
	v_fmamk_f32 v8, v8, 0x3c000000, v207
	v_mul_f32_e32 v9, 0x4f800000, v8
	v_cmp_gt_f32_e32 vcc, s63, v8
	s_nop 1
	v_cndmask_b32_e32 v10, v8, v9, vcc
	v_sqrt_f32_e32 v11, v10
	v_lshl_add_u64 v[8:9], s[40:41], 0, v[20:21]
	v_lshlrev_b64 v[8:9], 12, v[8:9]
	v_lshl_add_u64 v[16:17], v[2:3], 0, v[8:9]
	v_add_u32_e32 v8, -1, v11
	v_fma_f32 v9, -v8, v11, v10
	v_cmp_ge_f32_e64 s[4:5], 0, v9
	v_add_u32_e32 v9, 1, v11
	global_store_dwordx4 v[16:17], v[4:7], off nt
	v_cndmask_b32_e64 v8, v11, v8, s[4:5]
	v_fma_f32 v11, -v9, v11, v10
	v_cmp_lt_f32_e64 s[4:5], 0, v11
	s_nop 1
	v_cndmask_b32_e64 v8, v8, v9, s[4:5]
	v_mul_f32_e32 v9, 0x37800000, v8
	v_cndmask_b32_e32 v8, v8, v9, vcc
	v_cmp_class_f32_e32 vcc, v10, v224
	s_nop 1
	v_cndmask_b32_e32 v13, v8, v10, vcc
	v_lshlrev_b32_e32 v8, 8, v0
	v_and_b32_e32 v8, 0x1f00, v8
	v_div_scale_f32 v30, s[4:5], v13, v13, 1.0
	v_add_u32_e32 v20, v34, v8
	v_rcp_f32_e32 v31, v30
	ds_read_b128 v[8:11], v20
	ds_read_b128 v[4:7], v20 offset:32768
	v_fma_f32 v16, -v30, v31, 1.0
	v_fmac_f32_e32 v31, v16, v31
	s_waitcnt lgkmcnt(1)
	v_lshlrev_b32_e32 v16, 16, v11
	v_and_b32_e32 v17, 0xffff0000, v11
	v_lshlrev_b32_e32 v22, 16, v10
	v_and_b32_e32 v23, 0xffff0000, v10
	s_waitcnt lgkmcnt(0)
	v_lshlrev_b32_e32 v10, 16, v6
	v_and_b32_e32 v11, 0xffff0000, v6
	v_pk_fma_f32 v[10:11], v[186:187], v[10:11], v[22:23] neg_lo:[1,0,0] neg_hi:[1,0,0]
	v_lshlrev_b32_e32 v22, 16, v9
	v_and_b32_e32 v23, 0xffff0000, v9
	v_lshlrev_b32_e32 v28, 16, v8
	v_and_b32_e32 v29, 0xffff0000, v8
	v_lshlrev_b32_e32 v8, 16, v4
	v_and_b32_e32 v9, 0xffff0000, v4
	v_lshlrev_b32_e32 v26, 16, v5
	v_and_b32_e32 v27, 0xffff0000, v5
	v_pk_fma_f32 v[8:9], v[186:187], v[8:9], v[28:29] neg_lo:[1,0,0] neg_hi:[1,0,0]
	v_pk_fma_f32 v[22:23], v[186:187], v[26:27], v[22:23] neg_lo:[1,0,0] neg_hi:[1,0,0]
	v_pk_mul_f32 v[4:5], v[8:9], v[8:9]
	v_pk_mul_f32 v[26:27], v[22:23], v[22:23]
	v_add_f32_e32 v4, v4, v5
	v_add_f32_e32 v4, v26, v4
	v_lshlrev_b32_e32 v20, 16, v7
	v_and_b32_e32 v21, 0xffff0000, v7
	v_pk_mul_f32 v[6:7], v[10:11], v[10:11]
	v_add_f32_e32 v4, v27, v4
	v_pk_fma_f32 v[16:17], v[186:187], v[20:21], v[16:17] neg_lo:[1,0,0] neg_hi:[1,0,0]
	v_add_f32_e32 v4, v6, v4
	v_pk_mul_f32 v[20:21], v[16:17], v[16:17]
	v_add_f32_e32 v4, v7, v4
	v_add_f32_e32 v4, v20, v4
	v_add_f32_e32 v4, v21, v4
	s_nop 1
	v_mov_b32_dpp v5, v4 quad_perm:[1,0,3,2] row_mask:0xf bank_mask:0xf
	v_div_scale_f32 v6, vcc, 1.0, v13, 1.0
	v_mul_f32_e32 v7, v6, v31
	v_fma_f32 v20, -v30, v7, v6
	s_waitcnt lgkmcnt(0)
	v_add_f32_e32 v4, v4, v5
	s_nop 1
	v_mov_b32_dpp v5, v4 quad_perm:[2,3,0,1] row_mask:0xf bank_mask:0xf
	v_fmac_f32_e32 v7, v20, v31
	v_fma_f32 v6, -v30, v7, v6
	v_div_fmas_f32 v6, v6, v31, v7
	v_div_fixup_f32 v20, v6, v13, 1.0
	s_waitcnt lgkmcnt(0)
	v_add_f32_e32 v21, v4, v5
	s_nop 1
	v_mov_b32_dpp v26, v21 row_half_mirror row_mask:0xf bank_mask:0xf
	v_pk_mul_f32 v[4:5], v[32:33], v[20:21] op_sel_hi:[1,0]
	v_pk_mul_f32 v[6:7], v[24:25], v[20:21] op_sel_hi:[1,0]
	v_cvt_pk_bf16_f32 v4, v4, v5
	v_cvt_pk_bf16_f32 v5, v6, v7
	s_waitcnt lgkmcnt(0)
	v_add_f32_e32 v13, v21, v26
	s_nop 1
	v_mov_b32_dpp v21, v13 row_mirror row_mask:0xf bank_mask:0xf
	s_waitcnt lgkmcnt(0)
	v_pk_mul_f32 v[6:7], v[18:19], v[20:21] op_sel_hi:[1,0]
	s_nop 0
	v_cvt_pk_bf16_f32 v6, v6, v7
	v_add_f32_e32 v7, v13, v21
	v_fmamk_f32 v7, v7, 0x3c000000, v207
	v_mul_f32_e32 v13, 0x4f800000, v7
	v_cmp_gt_f32_e32 vcc, s63, v7
	v_pk_mul_f32 v[14:15], v[14:15], v[20:21] op_sel_hi:[1,0]
	s_nop 0
	v_cndmask_b32_e32 v18, v7, v13, vcc
	v_sqrt_f32_e32 v19, v18
	v_cvt_pk_bf16_f32 v7, v14, v15
	v_mov_b32_e32 v13, v1
	v_lshl_add_u64 v[12:13], s[40:41], 0, v[12:13]
	v_add_u32_e32 v14, -1, v19
	v_fma_f32 v15, -v14, v19, v18
	v_cmp_ge_f32_e64 s[4:5], 0, v15
	v_add_u32_e32 v15, 1, v19
	v_lshlrev_b64 v[12:13], 12, v[12:13]
	v_cndmask_b32_e64 v14, v19, v14, s[4:5]
	v_fma_f32 v19, -v15, v19, v18
	v_cmp_lt_f32_e64 s[4:5], 0, v19
	v_lshl_add_u64 v[12:13], v[2:3], 0, v[12:13]
	global_store_dwordx4 v[12:13], v[4:7], off nt
	v_cndmask_b32_e64 v14, v14, v15, s[4:5]
	v_mul_f32_e32 v15, 0x37800000, v14
	v_cndmask_b32_e32 v14, v14, v15, vcc
	v_cmp_class_f32_e32 vcc, v18, v224
	s_nop 1
	v_cndmask_b32_e32 v14, v14, v18, vcc
	v_div_scale_f32 v15, s[4:5], v14, v14, 1.0
	v_rcp_f32_e32 v18, v15
	s_mov_b64 s[4:5], 0
	v_fma_f32 v4, -v15, v18, 1.0
	v_fmac_f32_e32 v18, v4, v18
	v_div_scale_f32 v4, vcc, 1.0, v14, 1.0
	v_mul_f32_e32 v5, v4, v18
	v_fma_f32 v6, -v15, v5, v4
	v_fmac_f32_e32 v5, v6, v18
	v_fma_f32 v4, -v15, v5, v4
	v_div_fmas_f32 v4, v4, v18, v5
	v_div_fixup_f32 v12, v4, v14, 1.0
	v_pk_mul_f32 v[4:5], v[8:9], v[12:13] op_sel_hi:[1,0]
	v_pk_mul_f32 v[6:7], v[22:23], v[12:13] op_sel_hi:[1,0]
	v_cvt_pk_bf16_f32 v4, v4, v5
	v_cvt_pk_bf16_f32 v5, v6, v7
	v_pk_mul_f32 v[6:7], v[10:11], v[12:13] op_sel_hi:[1,0]
	v_pk_mul_f32 v[8:9], v[16:17], v[12:13] op_sel_hi:[1,0]
	v_cvt_pk_bf16_f32 v6, v6, v7
	v_cvt_pk_bf16_f32 v7, v8, v9
	v_lshl_add_u64 v[8:9], s[40:41], 0, v[0:1]
	v_lshlrev_b64 v[8:9], 12, v[8:9]
	v_lshl_add_u64 v[2:3], v[2:3], 0, v[8:9]
	global_store_dwordx4 v[2:3], v[4:7], off nt
	s_waitcnt lgkmcnt(0)
	s_barrier

.LBB0_418:
	s_ashr_i32 s4, s65, 3
	s_ashr_i32 s5, s4, 31
	s_lshl_b32 s75, s66, 7
	s_lshr_b32 s76, s68, 8
	s_and_b32 s71, s70, 3
	s_lshl_b64 s[40:41], s[4:5], 12
	s_ashr_i32 s38, s75, 31
	s_add_u32 s40, s40, s75
	s_addc_u32 s41, s41, s38
	s_lshl_b32 s38, s71, 5
	s_or_b32 s42, s40, s38
	s_mov_b32 s43, s41
	s_lshl_b32 s38, s65, 7
	s_lshl_b64 s[42:43], s[42:43], 11
	s_and_b32 s38, s38, 0x380
	s_lshl_b32 s50, s76, 6
	s_lshl_b64 s[4:5], s[4:5], 23
	s_add_u32 s44, s3, s4
	s_addc_u32 s45, s58, s5
	s_add_u32 s51, s16, s4
	s_addc_u32 s69, s17, s5
	s_lshl_b32 s74, s70, 10
	s_cmp_lg_u32 0, -1
	s_cselect_b32 s48, 0, 0
	s_add_i32 s72, s74, s48
	s_add_u32 s42, s10, s42
	s_addc_u32 s43, s11, s43
	s_lshl_b32 s38, s38, 1
	s_add_u32 s42, s42, s38
	s_addc_u32 s43, s43, 0
	s_lshl_b32 s48, s76, 7
	s_add_u32 s48, s42, s48
	s_addc_u32 s49, s43, 0
	s_add_u32 s44, s44, s38
	s_addc_u32 s45, s45, 0
	s_add_u32 s42, s51, s38
	s_addc_u32 s43, s69, 0
	s_lshl_b32 s69, s70, 4
	s_lshl_b32 s51, s71, 15
	global_load_dwordx4 v[14:17], v[38:39], off
	s_nop 0
	global_load_dwordx4 v[10:13], v[10:11], off offset:1024
	v_add_u32_e32 v226, s69, v215
	s_add_i32 s51, s51, s50
	s_add_i32 s73, s72, 0x10000
	global_load_dwordx4 v[40:43], v[192:193], off
	global_load_dwordx4 v[44:47], v[192:193], off offset:16
	global_load_dwordx4 v[48:51], v[194:195], off
	global_load_dwordx4 v[52:55], v[194:195], off offset:16
	global_load_dwordx4 v[66:69], v[196:197], off
	global_load_dwordx4 v[70:73], v[196:197], off offset:16
	s_mov_b32 s50, m0
	s_mov_b32 m0, s72
	s_nop 0
	global_load_lds_dwordx4 v226, s[44:45]
	s_mov_b32 m0, s50
	s_add_u32 s50, s44, 0x80
	v_add_u32_e32 v227, s51, v216
	s_addc_u32 s51, s45, 0
	s_add_i32 s77, s72, 0x2000
	s_mov_b32 s78, m0
	s_mov_b32 m0, s77
	s_nop 0
	global_load_lds_dwordx4 v226, s[50:51]
	s_mov_b32 m0, s78
	s_mov_b32 s50, m0
	s_mov_b32 m0, s73
	s_nop 0
	global_load_lds_dwordx4 v227, s[42:43]
	s_mov_b32 m0, s50
	s_add_u32 s50, s42, 0x80
	s_addc_u32 s51, s43, 0
	s_add_i32 s77, s72, 0x12000
	s_mov_b32 s78, m0
	s_mov_b32 m0, s77
	s_nop 0
	global_load_lds_dwordx4 v227, s[50:51]
	s_mov_b32 m0, s78
	s_add_u32 s50, s44, 0x20000
	s_addc_u32 s51, s45, 0
	s_add_i32 s77, s72, 0x4000
	s_mov_b32 s78, m0
	s_mov_b32 m0, s77
	s_nop 0
	global_load_lds_dwordx4 v226, s[50:51]
	s_mov_b32 m0, s78
	s_add_u32 s50, s44, 0x20080
	s_addc_u32 s51, s45, 0
	s_add_i32 s77, s72, 0x6000
	s_mov_b32 s78, m0
	s_mov_b32 m0, s77
	s_nop 0
	global_load_lds_dwordx4 v226, s[50:51]
	s_mov_b32 m0, s78
	v_lshlrev_b32_e32 v0, 1, v219
	global_load_dwordx4 v[120:123], v0, s[48:49]
	global_load_dwordx4 v[116:119], v0, s[48:49] offset:32
	global_load_dwordx4 v[112:115], v0, s[48:49] offset:64
	global_load_dwordx4 v[108:111], v0, s[48:49] offset:96
	s_add_u32 s48, s44, 0x40000
	s_addc_u32 s49, s45, 0
	s_add_i32 s50, s72, 0x8000
	s_mov_b32 s51, m0
	s_mov_b32 m0, s50
	s_nop 0
	global_load_lds_dwordx4 v226, s[48:49]
	s_mov_b32 m0, s51
	s_add_u32 s48, s44, 0x40080
	s_addc_u32 s49, s45, 0
	s_add_i32 s50, s72, 0xa000
	s_mov_b32 s51, m0
	s_mov_b32 m0, s50
	s_nop 0
	global_load_lds_dwordx4 v226, s[48:49]
	s_mov_b32 m0, s51
	s_waitcnt vmcnt(6) lgkmcnt(0)
	s_barrier
	v_lshlrev_b32_e32 v58, 16, v30
	v_and_b32_e32 v59, 0xffff0000, v30
	v_lshlrev_b32_e32 v60, 16, v31
	v_and_b32_e32 v61, 0xffff0000, v31
	v_lshlrev_b32_e32 v30, 16, v18
	v_and_b32_e32 v31, 0xffff0000, v18
	v_lshlrev_b32_e32 v18, 16, v19
	v_and_b32_e32 v19, 0xffff0000, v19
	v_lshlrev_b32_e32 v56, 16, v20
	v_and_b32_e32 v57, 0xffff0000, v20
	v_lshlrev_b32_e32 v62, 16, v32
	v_and_b32_e32 v63, 0xffff0000, v32
	v_lshlrev_b32_e32 v64, 16, v33
	v_and_b32_e32 v65, 0xffff0000, v33
	v_lshlrev_b32_e32 v32, 16, v22
	v_and_b32_e32 v33, 0xffff0000, v22
	v_lshlrev_b32_e32 v22, 16, v23
	v_and_b32_e32 v23, 0xffff0000, v23
	v_lshlrev_b32_e32 v74, 16, v24
	v_and_b32_e32 v75, 0xffff0000, v24
	v_lshlrev_b32_e32 v76, 16, v28
	v_and_b32_e32 v77, 0xffff0000, v28
	v_lshlrev_b32_e32 v24, 16, v25
	v_and_b32_e32 v25, 0xffff0000, v25
	v_lshlrev_b32_e32 v34, 16, v26
	v_and_b32_e32 v35, 0xffff0000, v26
	v_lshlrev_b32_e32 v26, 16, v27
	v_and_b32_e32 v27, 0xffff0000, v27
	s_lshl_b64 s[48:49], s[46:47], 12
	s_or_b32 s46, s46, 1
	s_and_b32 s47, s46, 0xfff
	s_cmp_lg_u32 s47, 1
	v_pk_fma_f32 v[30:31], v[40:41], v[30:31], 0 op_sel_hi:[1,1,0]
	v_pk_fma_f32 v[18:19], v[42:43], v[18:19], 0 op_sel_hi:[1,1,0]
	v_pk_fma_f32 v[40:41], v[44:45], v[56:57], 0 op_sel_hi:[1,1,0]
	v_pk_fma_f32 v[18:19], v[50:51], v[22:23], v[18:19]
	v_pk_fma_f32 v[22:23], v[52:53], v[74:75], v[40:41]
	v_pk_fma_f32 v[30:31], v[48:49], v[32:33], v[30:31]
	v_pk_fma_f32 v[22:23], v[70:71], v[62:63], v[22:23]
	v_pk_fma_f32 v[30:31], v[66:67], v[58:59], v[30:31]
	v_pk_mul_f32 v[22:23], v[22:23], v[76:77]
	v_pk_fma_f32 v[18:19], v[68:69], v[60:61], v[18:19]
	v_cvt_pk_bf16_f32 v20, v22, v23
	v_lshlrev_b32_e32 v22, 16, v21
	v_and_b32_e32 v23, 0xffff0000, v21
	v_pk_fma_f32 v[22:23], v[46:47], v[22:23], 0 op_sel_hi:[1,1,0]
	v_pk_mul_f32 v[30:31], v[30:31], v[34:35]
	v_pk_fma_f32 v[22:23], v[54:55], v[24:25], v[22:23]
	v_lshlrev_b32_e32 v24, 16, v29
	v_pk_fma_f32 v[22:23], v[72:73], v[64:65], v[22:23]
	v_and_b32_e32 v25, 0xffff0000, v29
	v_pk_mul_f32 v[26:27], v[18:19], v[26:27]
	v_pk_mul_f32 v[22:23], v[22:23], v[24:25]
	v_cvt_pk_bf16_f32 v18, v30, v31
	v_cvt_pk_bf16_f32 v19, v26, v27
	v_cvt_pk_bf16_f32 v21, v22, v23
	v_lshl_add_u64 v[44:45], v[204:205], 0, s[48:49]
	global_store_dwordx4 v[44:45], v[18:21], off offset:2048 nt
	global_load_dwordx4 v[18:21], v[192:193], off offset:2048
	s_nop 0
	global_load_dwordx4 v[22:25], v[192:193], off offset:2064
	global_load_dwordx4 v[26:29], v[198:199], off
	global_load_dwordx4 v[30:33], v[198:199], off offset:16
	global_load_dwordx4 v[40:43], v[200:201], off
	global_load_dwordx4 v[50:53], v[200:201], off offset:16
	v_lshlrev_b32_e32 v54, 16, v2
	v_and_b32_e32 v55, 0xffff0000, v2
	v_lshlrev_b32_e32 v2, 16, v3
	v_and_b32_e32 v3, 0xffff0000, v3
	v_lshlrev_b32_e32 v74, 16, v4
	v_and_b32_e32 v75, 0xffff0000, v4
	v_lshlrev_b32_e32 v4, 16, v5
	v_and_b32_e32 v5, 0xffff0000, v5
	v_lshlrev_b32_e32 v56, 16, v6
	v_and_b32_e32 v57, 0xffff0000, v6
	v_lshlrev_b32_e32 v6, 16, v7
	v_and_b32_e32 v7, 0xffff0000, v7
	v_lshlrev_b32_e32 v76, 16, v8
	v_and_b32_e32 v77, 0xffff0000, v8
	v_lshlrev_b32_e32 v8, 16, v9
	v_and_b32_e32 v9, 0xffff0000, v9
	v_lshlrev_b32_e32 v66, 16, v14
	v_and_b32_e32 v67, 0xffff0000, v14
	v_lshlrev_b32_e32 v68, 16, v15
	v_and_b32_e32 v69, 0xffff0000, v15
	v_lshlrev_b32_e32 v70, 16, v16
	v_and_b32_e32 v71, 0xffff0000, v16
	v_lshlrev_b32_e32 v72, 16, v17
	v_and_b32_e32 v73, 0xffff0000, v17
	v_lshlrev_b32_e32 v14, 16, v10
	v_and_b32_e32 v15, 0xffff0000, v10
	v_lshlrev_b32_e32 v10, 16, v11
	v_and_b32_e32 v11, 0xffff0000, v11
	v_lshlrev_b32_e32 v16, 16, v12
	v_and_b32_e32 v17, 0xffff0000, v12
	v_lshlrev_b32_e32 v12, 16, v13
	v_and_b32_e32 v13, 0xffff0000, v13
	v_mov_b32_e32 v34, 0
	v_mov_b32_e32 v46, 0
	v_mov_b32_e32 v47, 0
	v_mov_b32_e32 v48, 0
	s_cselect_b64 s[48:49], -1, 0
	s_cmp_eq_u32 s47, 1
	v_mov_b32_e32 v49, 0
	s_waitcnt vmcnt(5)
	v_pk_fma_f32 v[18:19], v[18:19], v[54:55], 0 op_sel_hi:[1,1,0]
	v_pk_fma_f32 v[2:3], v[20:21], v[2:3], 0 op_sel_hi:[1,1,0]
	s_waitcnt vmcnt(4)
	v_pk_fma_f32 v[20:21], v[22:23], v[74:75], 0 op_sel_hi:[1,1,0]
	v_pk_fma_f32 v[4:5], v[24:25], v[4:5], 0 op_sel_hi:[1,1,0]
	s_waitcnt vmcnt(3)
	v_pk_fma_f32 v[18:19], v[26:27], v[56:57], v[18:19]
	v_pk_fma_f32 v[2:3], v[28:29], v[6:7], v[2:3]
	s_waitcnt vmcnt(2)
	v_pk_fma_f32 v[6:7], v[30:31], v[76:77], v[20:21]
	v_pk_fma_f32 v[4:5], v[32:33], v[8:9], v[4:5]
	s_waitcnt vmcnt(1)
	v_pk_fma_f32 v[8:9], v[40:41], v[66:67], v[18:19]
	v_pk_fma_f32 v[2:3], v[42:43], v[68:69], v[2:3]
	s_waitcnt vmcnt(0)
	v_pk_fma_f32 v[6:7], v[50:51], v[70:71], v[6:7]
	v_pk_fma_f32 v[4:5], v[52:53], v[72:73], v[4:5]
	v_pk_mul_f32 v[8:9], v[8:9], v[14:15]
	v_pk_mul_f32 v[10:11], v[2:3], v[10:11]
	v_pk_mul_f32 v[6:7], v[6:7], v[16:17]
	v_pk_mul_f32 v[12:13], v[4:5], v[12:13]
	v_cvt_pk_bf16_f32 v2, v8, v9
	v_cvt_pk_bf16_f32 v3, v10, v11
	v_cvt_pk_bf16_f32 v4, v6, v7
	v_cvt_pk_bf16_f32 v5, v12, v13
	global_store_dwordx4 v[44:45], v[2:5], off offset:3072 nt
	s_cbranch_scc1 .LBB0_420
	global_load_dwordx4 v[46:49], v[36:37], off offset:-2048

.LBB0_424:
	global_load_dwordx4 v[74:77], v[192:193], off
	global_load_dwordx4 v[78:81], v[192:193], off offset:16
	global_load_dwordx4 v[82:85], v[194:195], off
	global_load_dwordx4 v[86:89], v[194:195], off offset:16
	global_load_dwordx4 v[90:93], v[196:197], off
	global_load_dwordx4 v[94:97], v[196:197], off offset:16
	s_waitcnt vmcnt(0) lgkmcnt(0)
	s_barrier
	s_waitcnt vmcnt(10)
	v_lshlrev_b32_e32 v98, 16, v46
	v_and_b32_e32 v99, 0xffff0000, v46
	v_lshlrev_b32_e32 v46, 16, v47
	v_and_b32_e32 v47, 0xffff0000, v47
	v_lshlrev_b32_e32 v104, 16, v48
	v_and_b32_e32 v105, 0xffff0000, v48
	v_lshlrev_b32_e32 v48, 16, v49
	v_and_b32_e32 v49, 0xffff0000, v49
	s_waitcnt vmcnt(9)
	v_lshlrev_b32_e32 v100, 16, v54
	v_and_b32_e32 v101, 0xffff0000, v54
	v_lshlrev_b32_e32 v54, 16, v55
	v_and_b32_e32 v55, 0xffff0000, v55
	v_lshlrev_b32_e32 v106, 16, v56
	v_and_b32_e32 v107, 0xffff0000, v56
	v_lshlrev_b32_e32 v56, 16, v57
	v_and_b32_e32 v57, 0xffff0000, v57
	s_waitcnt vmcnt(8)
	v_lshlrev_b32_e32 v102, 16, v50
	v_and_b32_e32 v103, 0xffff0000, v50
	v_lshlrev_b32_e32 v50, 16, v51
	v_and_b32_e32 v51, 0xffff0000, v51
	v_lshlrev_b32_e32 v124, 16, v52
	v_and_b32_e32 v125, 0xffff0000, v52
	v_lshlrev_b32_e32 v52, 16, v53
	v_and_b32_e32 v53, 0xffff0000, v53
	s_lshl_b64 s[46:47], s[46:47], 12
	v_lshl_add_u64 v[126:127], v[204:205], 0, s[46:47]
	s_add_u32 s46, s44, 0x60000
	s_addc_u32 s47, s45, 0
	s_cmp_lg_u32 0, -1
	s_cselect_b32 s48, 0, 0
	s_add_i32 s51, s48, s74
	s_add_i32 s74, s51, 0xc000
	s_add_u32 s44, s44, 0x60080
	s_addc_u32 s45, s45, 0
	s_add_i32 s75, s51, 0xe000
	s_add_u32 s48, s42, 0x20000
	s_addc_u32 s49, s43, 0
	s_add_i32 s76, s51, 0x14000
	s_add_u32 s42, s42, 0x20080
	s_addc_u32 s43, s43, 0
	s_add_i32 s51, s51, 0x16000
	s_cmp_lg_u32 s66, 0
	s_waitcnt vmcnt(5)
	v_pk_fma_f32 v[74:75], v[74:75], v[98:99], 0 op_sel_hi:[1,1,0]
	v_pk_fma_f32 v[46:47], v[76:77], v[46:47], 0 op_sel_hi:[1,1,0]
	s_waitcnt vmcnt(4)
	v_pk_fma_f32 v[76:77], v[78:79], v[104:105], 0 op_sel_hi:[1,1,0]
	v_pk_fma_f32 v[48:49], v[80:81], v[48:49], 0 op_sel_hi:[1,1,0]
	s_waitcnt vmcnt(3)
	v_pk_fma_f32 v[58:59], v[82:83], v[58:59], v[74:75]
	v_pk_fma_f32 v[46:47], v[84:85], v[60:61], v[46:47]
	s_waitcnt vmcnt(2)
	v_pk_fma_f32 v[60:61], v[86:87], v[62:63], v[76:77]
	v_pk_fma_f32 v[48:49], v[88:89], v[64:65], v[48:49]
	s_waitcnt vmcnt(1)
	v_pk_fma_f32 v[58:59], v[90:91], v[100:101], v[58:59]
	v_pk_fma_f32 v[46:47], v[92:93], v[54:55], v[46:47]
	s_waitcnt vmcnt(0)
	v_pk_fma_f32 v[54:55], v[94:95], v[106:107], v[60:61]
	v_pk_fma_f32 v[48:49], v[96:97], v[56:57], v[48:49]
	v_pk_mul_f32 v[56:57], v[58:59], v[102:103]
	v_pk_mul_f32 v[50:51], v[46:47], v[50:51]
	v_pk_mul_f32 v[54:55], v[54:55], v[124:125]
	v_pk_mul_f32 v[52:53], v[48:49], v[52:53]
	v_cvt_pk_bf16_f32 v46, v56, v57
	v_cvt_pk_bf16_f32 v47, v50, v51
	v_cvt_pk_bf16_f32 v48, v54, v55
	v_cvt_pk_bf16_f32 v49, v52, v53
	global_store_dwordx4 v[126:127], v[46:49], off offset:2048 nt
	global_load_dwordx4 v[46:49], v[192:193], off offset:2048
	s_nop 0
	global_load_dwordx4 v[50:53], v[192:193], off offset:2064
	global_load_dwordx4 v[54:57], v[198:199], off
	global_load_dwordx4 v[58:61], v[198:199], off offset:16
	global_load_dwordx4 v[62:65], v[200:201], off
	global_load_dwordx4 v[74:77], v[200:201], off offset:16
	v_lshlrev_b32_e32 v78, 16, v34
	v_and_b32_e32 v79, 0xffff0000, v34
	v_lshlrev_b32_e32 v34, 16, v35
	v_and_b32_e32 v35, 0xffff0000, v35
	v_lshlrev_b32_e32 v84, 16, v36
	v_and_b32_e32 v85, 0xffff0000, v36
	v_lshlrev_b32_e32 v36, 16, v37
	v_and_b32_e32 v37, 0xffff0000, v37
	v_lshlrev_b32_e32 v80, 16, v42
	v_and_b32_e32 v81, 0xffff0000, v42
	v_lshlrev_b32_e32 v42, 16, v43
	v_and_b32_e32 v43, 0xffff0000, v43
	v_lshlrev_b32_e32 v86, 16, v44
	v_and_b32_e32 v87, 0xffff0000, v44
	v_lshlrev_b32_e32 v44, 16, v45
	v_and_b32_e32 v45, 0xffff0000, v45
	v_lshlrev_b32_e32 v82, 16, v38
	v_and_b32_e32 v83, 0xffff0000, v38
	v_lshlrev_b32_e32 v38, 16, v39
	v_and_b32_e32 v39, 0xffff0000, v39
	v_lshlrev_b32_e32 v88, 16, v40
	v_and_b32_e32 v89, 0xffff0000, v40
	v_lshlrev_b32_e32 v40, 16, v41
	v_and_b32_e32 v41, 0xffff0000, v41
	s_waitcnt vmcnt(5)
	v_pk_fma_f32 v[46:47], v[46:47], v[78:79], 0 op_sel_hi:[1,1,0]
	v_pk_fma_f32 v[34:35], v[48:49], v[34:35], 0 op_sel_hi:[1,1,0]
	s_waitcnt vmcnt(4)
	v_pk_fma_f32 v[48:49], v[50:51], v[84:85], 0 op_sel_hi:[1,1,0]
	v_pk_fma_f32 v[36:37], v[52:53], v[36:37], 0 op_sel_hi:[1,1,0]
	s_waitcnt vmcnt(3)
	v_pk_fma_f32 v[46:47], v[54:55], v[66:67], v[46:47]
	v_pk_fma_f32 v[34:35], v[56:57], v[68:69], v[34:35]
	s_waitcnt vmcnt(2)
	v_pk_fma_f32 v[48:49], v[58:59], v[70:71], v[48:49]
	v_pk_fma_f32 v[36:37], v[60:61], v[72:73], v[36:37]
	s_waitcnt vmcnt(1)
	v_pk_fma_f32 v[46:47], v[62:63], v[80:81], v[46:47]
	v_pk_fma_f32 v[34:35], v[64:65], v[42:43], v[34:35]
	s_waitcnt vmcnt(0)
	v_pk_fma_f32 v[42:43], v[74:75], v[86:87], v[48:49]
	v_pk_fma_f32 v[36:37], v[76:77], v[44:45], v[36:37]
	v_pk_mul_f32 v[44:45], v[46:47], v[82:83]
	v_pk_mul_f32 v[38:39], v[34:35], v[38:39]
	v_pk_mul_f32 v[42:43], v[42:43], v[88:89]
	v_pk_mul_f32 v[40:41], v[36:37], v[40:41]
	v_cvt_pk_bf16_f32 v34, v44, v45
	v_cvt_pk_bf16_f32 v35, v38, v39
	v_cvt_pk_bf16_f32 v36, v42, v43
	v_cvt_pk_bf16_f32 v37, v40, v41
	global_store_dwordx4 v[126:127], v[34:37], off offset:3072 nt
	s_mov_b32 s77, m0
	s_mov_b32 m0, s74
	s_nop 0
	global_load_lds_dwordx4 v226, s[46:47]
	s_mov_b32 m0, s77
	s_mov_b32 s46, m0
	s_mov_b32 m0, s75
	s_nop 0
	global_load_lds_dwordx4 v226, s[44:45]
	s_mov_b32 m0, s46
	s_mov_b32 s44, m0
	s_mov_b32 m0, s76
	s_nop 0
	global_load_lds_dwordx4 v227, s[48:49]
	s_mov_b32 m0, s44
	s_nop 0
	s_mov_b32 s44, m0
	s_mov_b32 m0, s51
	s_nop 0
	global_load_lds_dwordx4 v227, s[42:43]
	s_mov_b32 m0, s44
	ds_read_b128 v[156:159], v228 offset:16384
	ds_read_b128 v[160:163], v228 offset:18432
	s_cbranch_scc0 .LBB0_473
	s_waitcnt vmcnt(5) lgkmcnt(0)
	s_barrier
	s_cbranch_execnz .LBB0_427

.LBB0_652:
	s_ashr_i32 s18, s3, 31
	s_lshr_b32 s18, s18, 26
	s_add_i32 s18, s3, s18
	s_ashr_i32 s20, s18, 6
	s_andn2_b32 s18, s18, 63
	s_lshl_b32 s21, s20, 11
	v_or_b32_e32 v16, s18, v4
	s_mul_i32 s22, s20, 0xff500000
	s_sub_i32 s20, s4, s21
	v_or_b32_e32 v18, 2, v16
	v_or_b32_e32 v20, 4, v16
	v_or_b32_e32 v22, 6, v16
	v_or_b32_e32 v24, 8, v16
	v_or_b32_e32 v26, 10, v16
	v_or_b32_e32 v28, 12, v16
	v_or_b32_e32 v30, 14, v16
	v_or_b32_e32 v32, 16, v16
	v_ashrrev_i32_e32 v17, 31, v16
	v_or_b32_e32 v34, 18, v16
	v_or_b32_e32 v36, 20, v16
	v_or_b32_e32 v38, 22, v16
	v_or_b32_e32 v40, 24, v16
	v_or_b32_e32 v42, 26, v16
	v_or_b32_e32 v44, 28, v16
	v_or_b32_e32 v46, 30, v16
	v_or_b32_e32 v48, 32, v16
	v_or_b32_e32 v50, 34, v16
	v_or_b32_e32 v52, 36, v16
	v_or_b32_e32 v54, 38, v16
	v_or_b32_e32 v56, 40, v16
	v_or_b32_e32 v58, 42, v16
	v_or_b32_e32 v60, 44, v16
	v_or_b32_e32 v62, 46, v16
	v_or_b32_e32 v64, 48, v16
	v_or_b32_e32 v66, 50, v16
	v_or_b32_e32 v68, 52, v16
	v_or_b32_e32 v70, 54, v16
	v_or_b32_e32 v72, 56, v16
	v_or_b32_e32 v74, 58, v16
	v_or_b32_e32 v76, 60, v16
	v_or_b32_e32 v78, 62, v16
	v_add_u32_e32 v82, s22, v6
	s_ashr_i32 s21, s20, 31
	v_ashrrev_i32_e32 v19, 31, v18
	v_ashrrev_i32_e32 v21, 31, v20
	v_ashrrev_i32_e32 v23, 31, v22
	v_ashrrev_i32_e32 v25, 31, v24
	v_ashrrev_i32_e32 v27, 31, v26
	v_ashrrev_i32_e32 v29, 31, v28
	v_ashrrev_i32_e32 v31, 31, v30
	v_ashrrev_i32_e32 v33, 31, v32
	s_ashr_i32 s19, s18, 31
	v_lshlrev_b64 v[16:17], 13, v[16:17]
	v_ashrrev_i32_e32 v35, 31, v34
	v_ashrrev_i32_e32 v37, 31, v36
	v_ashrrev_i32_e32 v39, 31, v38
	v_ashrrev_i32_e32 v41, 31, v40
	v_ashrrev_i32_e32 v43, 31, v42
	v_ashrrev_i32_e32 v45, 31, v44
	v_ashrrev_i32_e32 v47, 31, v46
	v_ashrrev_i32_e32 v49, 31, v48
	v_ashrrev_i32_e32 v51, 31, v50
	v_ashrrev_i32_e32 v53, 31, v52
	v_ashrrev_i32_e32 v55, 31, v54
	v_ashrrev_i32_e32 v57, 31, v56
	v_ashrrev_i32_e32 v59, 31, v58
	v_ashrrev_i32_e32 v61, 31, v60
	v_ashrrev_i32_e32 v63, 31, v62
	v_ashrrev_i32_e32 v65, 31, v64
	v_ashrrev_i32_e32 v67, 31, v66
	v_ashrrev_i32_e32 v69, 31, v68
	v_ashrrev_i32_e32 v71, 31, v70
	v_ashrrev_i32_e32 v73, 31, v72
	v_ashrrev_i32_e32 v75, 31, v74
	v_ashrrev_i32_e32 v77, 31, v76
	v_ashrrev_i32_e32 v79, 31, v78
	v_add_u32_e32 v84, 0xb000, v82
	v_add_u32_e32 v86, 0x16000, v82
	v_add_u32_e32 v88, 0x21000, v82
	v_lshl_add_u64 v[90:91], s[20:21], 2, v[0:1]
	v_lshlrev_b64 v[18:19], 13, v[18:19]
	v_lshlrev_b64 v[20:21], 13, v[20:21]
	v_lshlrev_b64 v[22:23], 13, v[22:23]
	v_lshlrev_b64 v[24:25], 13, v[24:25]
	v_lshlrev_b64 v[26:27], 13, v[26:27]
	v_lshlrev_b64 v[28:29], 13, v[28:29]
	v_lshlrev_b64 v[30:31], 13, v[30:31]
	v_lshlrev_b64 v[32:33], 13, v[32:33]
	v_lshl_add_u64 v[80:81], s[18:19], 1, v[2:3]
	v_ashrrev_i32_e32 v83, 31, v82
	v_lshlrev_b64 v[34:35], 13, v[34:35]
	v_lshlrev_b64 v[36:37], 13, v[36:37]
	v_lshlrev_b64 v[38:39], 13, v[38:39]
	v_lshlrev_b64 v[40:41], 13, v[40:41]
	v_lshlrev_b64 v[42:43], 13, v[42:43]
	v_lshlrev_b64 v[44:45], 13, v[44:45]
	v_lshlrev_b64 v[46:47], 13, v[46:47]
	v_lshlrev_b64 v[48:49], 13, v[48:49]
	v_lshlrev_b64 v[50:51], 13, v[50:51]
	v_lshlrev_b64 v[52:53], 13, v[52:53]
	v_lshlrev_b64 v[54:55], 13, v[54:55]
	v_lshlrev_b64 v[56:57], 13, v[56:57]
	v_lshlrev_b64 v[58:59], 13, v[58:59]
	v_lshlrev_b64 v[60:61], 13, v[60:61]
	v_lshlrev_b64 v[62:63], 13, v[62:63]
	v_lshlrev_b64 v[64:65], 13, v[64:65]
	v_lshlrev_b64 v[66:67], 13, v[66:67]
	v_lshlrev_b64 v[68:69], 13, v[68:69]
	v_lshlrev_b64 v[70:71], 13, v[70:71]
	v_lshlrev_b64 v[72:73], 13, v[72:73]
	v_lshlrev_b64 v[74:75], 13, v[74:75]
	v_lshlrev_b64 v[76:77], 13, v[76:77]
	v_lshlrev_b64 v[78:79], 13, v[78:79]
	v_ashrrev_i32_e32 v85, 31, v84
	v_ashrrev_i32_e32 v87, 31, v86
	v_ashrrev_i32_e32 v89, 31, v88
	v_lshl_add_u64 v[16:17], v[90:91], 0, v[16:17]
	v_lshl_add_u64 v[18:19], v[90:91], 0, v[18:19]
	v_lshl_add_u64 v[20:21], v[90:91], 0, v[20:21]
	v_lshl_add_u64 v[22:23], v[90:91], 0, v[22:23]
	v_lshl_add_u64 v[24:25], v[90:91], 0, v[24:25]
	v_lshl_add_u64 v[26:27], v[90:91], 0, v[26:27]
	v_lshl_add_u64 v[28:29], v[90:91], 0, v[28:29]
	v_lshl_add_u64 v[30:31], v[90:91], 0, v[30:31]
	v_lshl_add_u64 v[32:33], v[90:91], 0, v[32:33]
	v_lshl_add_u64 v[82:83], v[82:83], 1, v[80:81]
	v_lshl_add_u64 v[34:35], v[90:91], 0, v[34:35]
	v_lshl_add_u64 v[36:37], v[90:91], 0, v[36:37]
	v_lshl_add_u64 v[38:39], v[90:91], 0, v[38:39]
	v_lshl_add_u64 v[40:41], v[90:91], 0, v[40:41]
	v_lshl_add_u64 v[42:43], v[90:91], 0, v[42:43]
	v_lshl_add_u64 v[44:45], v[90:91], 0, v[44:45]
	v_lshl_add_u64 v[46:47], v[90:91], 0, v[46:47]
	v_lshl_add_u64 v[48:49], v[90:91], 0, v[48:49]
	v_lshl_add_u64 v[50:51], v[90:91], 0, v[50:51]
	v_lshl_add_u64 v[52:53], v[90:91], 0, v[52:53]
	v_lshl_add_u64 v[54:55], v[90:91], 0, v[54:55]
	v_lshl_add_u64 v[56:57], v[90:91], 0, v[56:57]
	v_lshl_add_u64 v[58:59], v[90:91], 0, v[58:59]
	v_lshl_add_u64 v[60:61], v[90:91], 0, v[60:61]
	v_lshl_add_u64 v[62:63], v[90:91], 0, v[62:63]
	v_lshl_add_u64 v[64:65], v[90:91], 0, v[64:65]
	v_lshl_add_u64 v[66:67], v[90:91], 0, v[66:67]
	v_lshl_add_u64 v[68:69], v[90:91], 0, v[68:69]
	v_lshl_add_u64 v[70:71], v[90:91], 0, v[70:71]
	v_lshl_add_u64 v[72:73], v[90:91], 0, v[72:73]
	v_lshl_add_u64 v[74:75], v[90:91], 0, v[74:75]
	v_lshl_add_u64 v[76:77], v[90:91], 0, v[76:77]
	v_lshl_add_u64 v[78:79], v[90:91], 0, v[78:79]
	v_lshl_add_u64 v[84:85], v[84:85], 1, v[80:81]
	v_lshl_add_u64 v[86:87], v[86:87], 1, v[80:81]
	v_lshl_add_u64 v[80:81], v[88:89], 1, v[80:81]
	global_load_dword v15, v[16:17], off nt
	global_load_dword v88, v[18:19], off nt
	global_load_dword v89, v[20:21], off nt
	global_load_dword v90, v[22:23], off nt
	global_load_dword v91, v[24:25], off nt
	global_load_dword v92, v[26:27], off nt
	global_load_dword v93, v[28:29], off nt
	global_load_dword v94, v[30:31], off nt
	global_load_dword v95, v[32:33], off nt
	global_load_dword v96, v[34:35], off nt
	global_load_dword v97, v[36:37], off nt
	global_load_dword v98, v[38:39], off nt
	global_load_dword v99, v[40:41], off nt
	global_load_dword v100, v[42:43], off nt
	global_load_dword v101, v[44:45], off nt
	global_load_dword v16, v[46:47], off nt
	global_load_dword v17, v[48:49], off nt
	global_load_dword v18, v[50:51], off nt
	global_load_dword v19, v[52:53], off nt
	global_load_dword v20, v[54:55], off nt
	global_load_dword v21, v[56:57], off nt
	global_load_dword v22, v[58:59], off nt
	global_load_dword v23, v[60:61], off nt
	global_load_dword v24, v[62:63], off nt
	global_load_dword v25, v[64:65], off nt
	global_load_dword v26, v[66:67], off nt
	global_load_dword v27, v[68:69], off nt
	global_load_dword v28, v[70:71], off nt
	global_load_dword v29, v[72:73], off nt
	global_load_dword v30, v[74:75], off nt
	global_load_dword v31, v[76:77], off nt
	global_load_dword v32, v[78:79], off nt
	s_waitcnt vmcnt(0)
	ds_write2_b32 v7, v15, v88 offset1:66
	ds_write2_b32 v7, v89, v90 offset0:132 offset1:198
	ds_write2_b32 v8, v91, v92 offset0:8 offset1:74
	ds_write2_b32 v8, v93, v94 offset0:140 offset1:206
	ds_write2_b32 v9, v95, v96 offset0:16 offset1:82
	ds_write2_b32 v9, v97, v98 offset0:148 offset1:214
	ds_write2_b32 v10, v99, v100 offset0:24 offset1:90
	ds_write2_b32 v10, v101, v16 offset0:156 offset1:222
	ds_write2_b32 v11, v17, v18 offset0:32 offset1:98
	ds_write2_b32 v11, v19, v20 offset0:164 offset1:230
	ds_write2_b32 v12, v21, v22 offset0:40 offset1:106
	ds_write2_b32 v12, v23, v24 offset0:172 offset1:238
	ds_write2_b32 v13, v25, v26 offset0:48 offset1:114
	ds_write2_b32 v13, v27, v28 offset0:180 offset1:246
	ds_write2_b32 v14, v29, v30 offset0:56 offset1:122
	ds_write2_b32 v14, v31, v32 offset0:188 offset1:254
	s_waitcnt lgkmcnt(0)
	ds_read2_b32 v[16:17], v5 offset0:33 offset1:41
	ds_read2_b32 v[18:19], v5 offset1:8
	ds_read2_b32 v[20:21], v5 offset0:66 offset1:74
	ds_read2_b32 v[22:23], v5 offset0:99 offset1:107
	ds_read2_b32 v[24:25], v5 offset0:132 offset1:140
	ds_read2_b32 v[26:27], v5 offset0:165 offset1:173
	ds_read2_b32 v[28:29], v5 offset0:198 offset1:206
	ds_read2_b32 v[30:31], v5 offset0:231 offset1:239
	ds_read2_b32 v[32:33], v5 offset0:49 offset1:57
	ds_read2_b32 v[34:35], v5 offset0:16 offset1:24
	ds_read2_b32 v[36:37], v5 offset0:82 offset1:90
	ds_read2_b32 v[38:39], v5 offset0:115 offset1:123
	ds_read2_b32 v[40:41], v5 offset0:148 offset1:156
	ds_read2_b32 v[42:43], v5 offset0:181 offset1:189
	ds_read2_b32 v[44:45], v5 offset0:214 offset1:222
	ds_read2_b32 v[46:47], v5 offset0:247 offset1:255
	s_waitcnt lgkmcnt(14)
	v_bfe_u32 v15, v18, 16, 1
	s_waitcnt lgkmcnt(13)
	v_bfe_u32 v49, v20, 16, 1
	s_waitcnt lgkmcnt(12)
	v_bfe_u32 v50, v22, 16, 1
	s_waitcnt lgkmcnt(11)
	v_bfe_u32 v51, v24, 16, 1
	s_waitcnt lgkmcnt(10)
	v_bfe_u32 v52, v26, 16, 1
	s_waitcnt lgkmcnt(9)
	v_bfe_u32 v53, v28, 16, 1
	v_bfe_u32 v48, v16, 16, 1
	s_waitcnt lgkmcnt(8)
	v_bfe_u32 v54, v30, 16, 1
	v_bfe_u32 v55, v19, 16, 1
	v_bfe_u32 v56, v17, 16, 1
	v_bfe_u32 v57, v21, 16, 1
	v_bfe_u32 v58, v23, 16, 1
	v_bfe_u32 v59, v25, 16, 1
	v_bfe_u32 v60, v27, 16, 1
	v_bfe_u32 v61, v29, 16, 1
	v_bfe_u32 v62, v31, 16, 1
	s_waitcnt lgkmcnt(6)
	v_bfe_u32 v63, v34, 16, 1
	s_waitcnt lgkmcnt(5)
	v_bfe_u32 v65, v36, 16, 1
	s_waitcnt lgkmcnt(4)
	v_bfe_u32 v66, v38, 16, 1
	s_waitcnt lgkmcnt(3)
	v_bfe_u32 v67, v40, 16, 1
	s_waitcnt lgkmcnt(2)
	v_bfe_u32 v68, v42, 16, 1
	s_waitcnt lgkmcnt(1)
	v_bfe_u32 v69, v44, 16, 1
	v_bfe_u32 v71, v35, 16, 1
	v_bfe_u32 v73, v37, 16, 1
	v_bfe_u32 v75, v41, 16, 1
	v_bfe_u32 v77, v45, 16, 1
	v_add3_u32 v15, v18, v15, s6
	v_add3_u32 v18, v20, v49, s6
	v_add3_u32 v20, v22, v50, s6
	v_add3_u32 v22, v24, v51, s6
	v_add3_u32 v24, v26, v52, s6
	v_add3_u32 v26, v28, v53, s6
	v_bfe_u32 v64, v32, 16, 1
	s_waitcnt lgkmcnt(0)
	v_bfe_u32 v70, v46, 16, 1
	v_bfe_u32 v72, v33, 16, 1
	v_bfe_u32 v74, v39, 16, 1
	v_bfe_u32 v76, v43, 16, 1
	v_bfe_u32 v78, v47, 16, 1
	v_add3_u32 v16, v16, v48, s6
	v_add3_u32 v28, v30, v54, s6
	v_add3_u32 v19, v19, v55, s6
	v_add3_u32 v30, v17, v56, s6
	v_add3_u32 v17, v21, v57, s6
	v_add3_u32 v21, v23, v58, s6
	v_add3_u32 v23, v25, v59, s6
	v_add3_u32 v25, v27, v60, s6
	v_add3_u32 v27, v29, v61, s6
	v_add3_u32 v29, v31, v62, s6
	v_add3_u32 v31, v34, v63, s6
	v_add3_u32 v34, v36, v65, s6
	v_add3_u32 v36, v38, v66, s6
	v_add3_u32 v38, v40, v67, s6
	v_add3_u32 v40, v42, v68, s6
	v_add3_u32 v42, v44, v69, s6
	v_add3_u32 v35, v35, v71, s6
	v_add3_u32 v37, v37, v73, s6
	v_add3_u32 v41, v41, v75, s6
	v_add3_u32 v45, v45, v77, s6
	v_lshrrev_b32_e32 v15, 16, v15
	v_lshrrev_b32_e32 v18, 16, v18
	v_lshrrev_b32_e32 v22, 16, v22
	v_lshrrev_b32_e32 v26, 16, v26
	v_add3_u32 v32, v32, v64, s6
	v_add3_u32 v44, v46, v70, s6
	v_add3_u32 v33, v33, v72, s6
	v_add3_u32 v39, v39, v74, s6
	v_add3_u32 v43, v43, v76, s6
	v_add3_u32 v46, v47, v78, s6
	v_lshrrev_b32_e32 v47, 16, v19
	v_lshrrev_b32_e32 v48, 16, v17
	v_lshrrev_b32_e32 v23, 16, v23
	v_lshrrev_b32_e32 v27, 16, v27
	v_lshrrev_b32_e32 v31, 16, v31
	v_lshrrev_b32_e32 v34, 16, v34
	v_lshrrev_b32_e32 v38, 16, v38
	v_lshrrev_b32_e32 v42, 16, v42
	v_lshrrev_b32_e32 v35, 16, v35
	v_lshrrev_b32_e32 v37, 16, v37
	v_lshrrev_b32_e32 v41, 16, v41
	v_lshrrev_b32_e32 v45, 16, v45
	v_and_or_b32 v16, v16, s7, v15
	v_and_or_b32 v17, v20, s7, v18
	v_and_or_b32 v18, v24, s7, v22
	v_and_or_b32 v19, v28, s7, v26
	v_and_or_b32 v20, v30, s7, v47
	v_and_or_b32 v21, v21, s7, v48
	v_and_or_b32 v22, v25, s7, v23
	v_and_or_b32 v23, v29, s7, v27
	v_and_or_b32 v24, v32, s7, v31
	v_and_or_b32 v25, v36, s7, v34
	v_and_or_b32 v26, v40, s7, v38
	v_and_or_b32 v27, v44, s7, v42
	v_and_or_b32 v28, v33, s7, v35
	v_and_or_b32 v29, v39, s7, v37
	v_and_or_b32 v30, v43, s7, v41
	v_and_or_b32 v31, v46, s7, v45
	global_store_dwordx4 v[82:83], v[16:19], off nt
	global_store_dwordx4 v[84:85], v[20:23], off nt
	global_store_dwordx4 v[86:87], v[24:27], off nt
	global_store_dwordx4 v[80:81], v[28:31], off nt
	s_waitcnt lgkmcnt(0)
	s_add_i32 s3, s3, s0
	s_add_i32 s4, s4, s5
	s_cmpk_lt_i32 s3, 0x1600
	v_add_u32_e32 v6, s1, v6
	s_cbranch_scc1 .LBB0_652
